# work queue: for DSA items on queue-2-first workgroups the next-item counter add is issued at the start of the top-k phase and consumed before the gathers (was a synchronous round trip at the loop top)
# baseline (speedup 1.0000x reference)
;     ...
;     auto fetch = [&]() -> int {
;         auto q1 = [&](int i) -> int { return i < N_A + N_C ? N_D + N_B + i : N_D + (i - (N_A + N_C)); };
;         if (pref == 0) { int i = (int)atomicAdd(ctr, 1u); if (i < N_D) return i; i = (int)atomicAdd(ctr + 32, 1u); return i < N_ALL - N_D ? q1(i) : N_ALL; }
;         int i = (int)atomicAdd(ctr + 32, 1u); if (i < N_ALL - N_D) return q1(i); i = (int)atomicAdd(ctr, 1u); return i < N_D ? i : N_ALL; };
;     int nxt = 0;
;     if (threadIdx.x == 0) nxt = fetch();
;     for (;;) {
;         __syncthreads();
;         if (threadIdx.x == 0) *sitem = nxt;
;         __syncthreads();
;         const int it = __builtin_amdgcn_readfirstlane(*sitem);
;         if (threadIdx.x == 0 && it < N_ALL) nxt = fetch();
.LBB0_136:
	s_or_b64 exec, exec, s[0:1]
	v_readlane_b32 s0, v253, 40
	s_waitcnt lgkmcnt(0)
	s_barrier
	v_mov_b32_e32 v0, s0
	ds_read_b32 v0, v0
	v_readlane_b32 s20, v251, 13
	v_readlane_b32 s21, v251, 14
	s_waitcnt lgkmcnt(0)
	v_readfirstlane_b32 s58, v0
	s_cmpk_lt_i32 s58, 0xa00
	s_cselect_b64 s[0:1], -1, 0
	s_and_b64 s[20:21], s[20:21], s[0:1]
	s_and_saveexec_b64 s[0:1], s[20:21]
	s_cbranch_execz .LBB0_147
	v_readlane_b32 s20, v253, 57
	v_readlane_b32 s21, v253, 58
	s_and_b64 vcc, exec, s[20:21]
	s_cbranch_vccz .LBB0_169
	s_cmpk_gt_i32 s58, 0xff
	s_cbranch_scc0 .Ldf_fetch_now
	s_cmpk_lt_i32 s58, 0x900
	s_cbranch_scc1 .LBB0_147
.Ldf_fetch_now:
	s_mov_b64 s[22:23], exec
	v_mbcnt_lo_u32_b32 v0, s22, 0
	v_mbcnt_hi_u32_b32 v0, s23, v0
	v_cmp_eq_u32_e32 vcc, 0, v0
	s_and_saveexec_b64 s[20:21], vcc
	s_cbranch_execz .LBB0_140
	s_bcnt1_i32_b64 s22, s[22:23]
	v_mov_b32_e32 v2, s22
	v_readlane_b32 s22, v253, 55
	v_readlane_b32 s23, v253, 56
	s_nop 4
	global_atomic_add v2, v1, v2, s[22:23] offset:128 sc0

; __device__ __forceinline__ unsigned sortable(float f) { const unsigned b = __float_as_uint(f); return (b & 0x80000000u) ? ~b : (b | 0x80000000u); }
;     ...
; #pragma unroll
;       for (int r = 0; r < 64; ++r) { u[r] = 0u; if (r * 64 < n) { const float f = srow[r * 64 + lane]; u[r] = (r * 64 + lane < n) ? sortable(f) : 0u; } }
;       const int nreg = (n + 63) >> 6;
.LBB0_198:
	s_add_i32 s61, s64, s30
	s_lshl_b32 s0, s64, 14
	s_add_i32 s60, s0, 0
	v_cmp_lt_i32_e64 s[0:1], s61, v163
	v_cmp_ge_i32_e32 vcc, s61, v163
	v_mov_b32_e32 v5, 0
	v_writelane_b32 v254, s0, 0
	v_mov_b32_e32 v6, 0
	s_waitcnt lgkmcnt(0)
	v_writelane_b32 v254, s1, 1
	s_barrier
	s_cmp_gt_i32 s61, 63
	s_cselect_b64 s[0:1], -1, 0
	v_writelane_b32 v254, s0, 2
	s_nop 1
	v_writelane_b32 v254, s1, 3
	s_cmpk_gt_i32 s61, 0x7f
	s_cselect_b64 s[0:1], -1, 0
	v_writelane_b32 v254, s0, 4
	s_nop 1
	v_writelane_b32 v254, s1, 5
	s_cmpk_gt_i32 s61, 0xbf
	s_cselect_b64 s[0:1], -1, 0
	v_writelane_b32 v254, s0, 6
	s_nop 1
	v_writelane_b32 v254, s1, 7
	s_cmpk_gt_i32 s61, 0xff
	s_cselect_b64 s[0:1], -1, 0
	v_writelane_b32 v254, s0, 8
	s_nop 1
	v_writelane_b32 v254, s1, 9
	s_cmpk_gt_i32 s61, 0x13f
	s_cselect_b64 s[0:1], -1, 0
	v_writelane_b32 v254, s0, 10
	s_nop 1
	v_writelane_b32 v254, s1, 11
	s_cmpk_gt_i32 s61, 0x17f
	s_cselect_b64 s[0:1], -1, 0
	v_writelane_b32 v254, s0, 12
	s_nop 1
	v_writelane_b32 v254, s1, 13
	s_cmpk_gt_i32 s61, 0x1bf
	s_cselect_b64 s[0:1], -1, 0
	v_writelane_b32 v254, s0, 14
	s_nop 1
	v_writelane_b32 v254, s1, 15
	s_cmpk_gt_i32 s61, 0x1ff
	s_cselect_b64 s[0:1], -1, 0
	v_writelane_b32 v254, s0, 16
	s_nop 1
	v_writelane_b32 v254, s1, 17
	s_cmpk_gt_i32 s61, 0x23f
	s_cselect_b64 s[0:1], -1, 0
	v_writelane_b32 v254, s0, 18
	s_nop 1
	v_writelane_b32 v254, s1, 19
	s_cmpk_gt_i32 s61, 0x27f
	s_cselect_b64 s[0:1], -1, 0
	v_writelane_b32 v254, s0, 20
	s_nop 1
	v_writelane_b32 v254, s1, 21
	s_cmpk_gt_i32 s61, 0x2bf
	s_cselect_b64 s[0:1], -1, 0
	v_writelane_b32 v254, s0, 22
	s_nop 1
	v_writelane_b32 v254, s1, 23
	s_cmpk_gt_i32 s61, 0x2ff
	s_cselect_b64 s[0:1], -1, 0
	v_writelane_b32 v254, s0, 24
	s_nop 1
	v_writelane_b32 v254, s1, 25
	s_cmpk_gt_i32 s61, 0x33f
	s_cselect_b64 s[0:1], -1, 0
	v_writelane_b32 v254, s0, 26
	s_nop 1
	v_writelane_b32 v254, s1, 27
	s_cmpk_gt_i32 s61, 0x37f
	s_cselect_b64 s[0:1], -1, 0
	v_writelane_b32 v254, s0, 28
	s_nop 1
	v_writelane_b32 v254, s1, 29
	s_cmpk_gt_i32 s61, 0x3bf
	s_cselect_b64 s[0:1], -1, 0
	v_writelane_b32 v254, s0, 30
	s_nop 1
	v_writelane_b32 v254, s1, 31
	s_cmpk_gt_i32 s61, 0x3ff
	s_cselect_b64 s[0:1], -1, 0
	v_writelane_b32 v254, s0, 32
	s_nop 1
	v_writelane_b32 v254, s1, 33
	s_cmpk_gt_i32 s61, 0x43f
	s_cselect_b64 s[0:1], -1, 0
	v_writelane_b32 v254, s0, 34
	s_nop 1
	v_writelane_b32 v254, s1, 35
	s_cmpk_gt_i32 s61, 0x47f
	s_cselect_b64 s[0:1], -1, 0
	v_writelane_b32 v254, s0, 36
	s_nop 1
	v_writelane_b32 v254, s1, 37
	s_cmpk_gt_i32 s61, 0x4bf
	s_cselect_b64 s[0:1], -1, 0
	v_writelane_b32 v254, s0, 38
	s_nop 1
	v_writelane_b32 v254, s1, 39
	s_cmpk_gt_i32 s61, 0x4ff
	s_cselect_b64 s[0:1], -1, 0
	v_writelane_b32 v254, s0, 40
	s_nop 1
	v_writelane_b32 v254, s1, 41
	s_cmpk_gt_i32 s61, 0x53f
	s_cselect_b64 s[0:1], -1, 0
	v_writelane_b32 v254, s0, 42
	s_nop 1
	v_writelane_b32 v254, s1, 43
	s_cmpk_gt_i32 s61, 0x57f
	s_cselect_b64 s[0:1], -1, 0
	v_writelane_b32 v254, s0, 44
	s_nop 1
	v_writelane_b32 v254, s1, 45
	s_cmpk_gt_i32 s61, 0x5bf
	s_cselect_b64 s[0:1], -1, 0
	v_writelane_b32 v254, s0, 46
	s_nop 1
	v_writelane_b32 v254, s1, 47
	s_cmpk_gt_i32 s61, 0x5ff
	s_cselect_b64 s[0:1], -1, 0
	v_writelane_b32 v254, s0, 48
	s_nop 1
	v_writelane_b32 v254, s1, 49
	s_cmpk_gt_i32 s61, 0x63f
	s_cselect_b64 s[0:1], -1, 0
	v_writelane_b32 v254, s0, 50
	s_nop 1
	v_writelane_b32 v254, s1, 51
	s_cmpk_gt_i32 s61, 0x67f
	s_cselect_b64 s[0:1], -1, 0
	v_writelane_b32 v254, s0, 52
	s_nop 1
	v_writelane_b32 v254, s1, 53
	s_cmpk_gt_i32 s61, 0x6bf
	s_cselect_b64 s[0:1], -1, 0
	v_writelane_b32 v254, s0, 54
	s_nop 1
	v_writelane_b32 v254, s1, 55
	s_cmpk_gt_i32 s61, 0x6ff
	s_cselect_b64 s[0:1], -1, 0
	v_writelane_b32 v254, s0, 56
	s_nop 1
	v_writelane_b32 v254, s1, 57
	s_cmpk_gt_i32 s61, 0x73f
	s_cselect_b64 s[0:1], -1, 0
	v_writelane_b32 v254, s0, 58
	s_nop 1
	v_writelane_b32 v254, s1, 59
	s_cmpk_gt_i32 s61, 0x77f
	s_cselect_b64 s[0:1], -1, 0
	v_writelane_b32 v254, s0, 60
	s_nop 1
	v_writelane_b32 v254, s1, 61
	s_cmpk_gt_i32 s61, 0x7bf
	s_cselect_b64 s[0:1], -1, 0
	v_writelane_b32 v254, s0, 62
	s_nop 1
	v_writelane_b32 v254, s1, 63
	s_cmpk_gt_i32 s61, 0x7ff
	s_cselect_b64 s[0:1], -1, 0
	v_writelane_b32 v250, s0, 0
	s_nop 1
	v_writelane_b32 v250, s1, 1
	s_cmpk_gt_i32 s61, 0x83f
	s_cselect_b64 s[0:1], -1, 0
	v_writelane_b32 v250, s0, 2
	s_nop 1
	v_writelane_b32 v250, s1, 3
	s_cmpk_gt_i32 s61, 0x87f
	s_cselect_b64 s[0:1], -1, 0
	v_writelane_b32 v250, s0, 4
	s_nop 1
	v_writelane_b32 v250, s1, 5
	s_cmpk_gt_i32 s61, 0x8bf
	s_cselect_b64 s[0:1], -1, 0
	v_writelane_b32 v250, s0, 6
	s_nop 1
	v_writelane_b32 v250, s1, 7
	s_cmpk_gt_i32 s61, 0x8ff
	s_cselect_b64 s[0:1], -1, 0
	v_writelane_b32 v250, s0, 8
	s_nop 1
	v_writelane_b32 v250, s1, 9
	s_cmpk_gt_i32 s61, 0x93f
	s_cselect_b64 s[0:1], -1, 0
	v_writelane_b32 v250, s0, 10
	s_nop 1
	v_writelane_b32 v250, s1, 11
	s_cmpk_gt_i32 s61, 0x97f
	s_cselect_b64 s[0:1], -1, 0
	v_writelane_b32 v250, s0, 12
	s_nop 1
	v_writelane_b32 v250, s1, 13
	s_cmpk_gt_i32 s61, 0x9bf
	s_cselect_b64 s[0:1], -1, 0
	v_writelane_b32 v250, s0, 14
	s_nop 1
	v_writelane_b32 v250, s1, 15
	s_cmpk_gt_i32 s61, 0x9ff
	s_cselect_b64 s[0:1], -1, 0
	v_writelane_b32 v250, s0, 16
	s_nop 1
	v_writelane_b32 v250, s1, 17
	s_cmpk_gt_i32 s61, 0xa3f
	s_cselect_b64 s[0:1], -1, 0
	v_writelane_b32 v250, s0, 18
	s_nop 1
	v_writelane_b32 v250, s1, 19
	s_cmpk_gt_i32 s61, 0xa7f
	s_cselect_b64 s[0:1], -1, 0
	v_writelane_b32 v250, s0, 20
	s_nop 1
	v_writelane_b32 v250, s1, 21
	s_cmpk_gt_i32 s61, 0xabf
	s_cselect_b64 s[0:1], -1, 0
	v_writelane_b32 v250, s0, 22
	s_nop 1
	v_writelane_b32 v250, s1, 23
	s_cmpk_gt_i32 s61, 0xaff
	s_cselect_b64 s[0:1], -1, 0
	v_writelane_b32 v250, s0, 24
	s_nop 1
	v_writelane_b32 v250, s1, 25
	s_cmpk_gt_i32 s61, 0xb3f
	s_cselect_b64 s[0:1], -1, 0
	v_writelane_b32 v250, s0, 26
	s_nop 1
	v_writelane_b32 v250, s1, 27
	s_cmpk_gt_i32 s61, 0xb7f
	s_cselect_b64 s[0:1], -1, 0
	v_writelane_b32 v250, s0, 28
	s_nop 1
	v_writelane_b32 v250, s1, 29
	s_cmpk_gt_i32 s61, 0xbbf
	s_cselect_b64 s[0:1], -1, 0
	v_writelane_b32 v250, s0, 30
	s_nop 1
	v_writelane_b32 v250, s1, 31
	s_cmpk_gt_i32 s61, 0xbff
	s_cselect_b64 s[52:53], -1, 0
	s_cmpk_gt_i32 s61, 0xc3f
	s_cselect_b64 s[50:51], -1, 0
	s_cmpk_gt_i32 s61, 0xc7f
	s_cselect_b64 s[48:49], -1, 0
	s_cmpk_gt_i32 s61, 0xcbf
	s_cselect_b64 s[46:47], -1, 0
	s_cmpk_gt_i32 s61, 0xcff
	s_cselect_b64 s[42:43], -1, 0
	s_cmpk_gt_i32 s61, 0xd3f
	s_cselect_b64 s[40:41], -1, 0
	s_cmpk_gt_i32 s61, 0xd7f
	s_cselect_b64 s[38:39], -1, 0
	s_cmpk_gt_i32 s61, 0xdbf
	s_cselect_b64 s[82:83], -1, 0
	s_cmpk_gt_i32 s61, 0xdff
	s_cselect_b64 s[96:97], -1, 0
	s_cmpk_gt_i32 s61, 0xe3f
	s_cselect_b64 s[94:95], -1, 0
	s_cmpk_gt_i32 s61, 0xe7f
	s_cselect_b64 s[92:93], -1, 0
	s_cmpk_gt_i32 s61, 0xebf
	s_cselect_b64 s[76:77], -1, 0
	s_cmpk_gt_i32 s61, 0xeff
	s_cselect_b64 s[90:91], -1, 0
	s_cmpk_gt_i32 s61, 0xf3f
	s_cselect_b64 s[88:89], -1, 0
	s_cmpk_gt_i32 s61, 0xf7f
	s_cselect_b64 s[86:87], -1, 0
	s_cmpk_gt_i32 s61, 0xfbf
	s_cselect_b64 s[84:85], -1, 0
	s_waitcnt vmcnt(0)
; #define LAS __attribute__((address_space(3)))
; __device__ __forceinline__ unsigned sortable(float f) { const unsigned b = __float_as_uint(f); return (b & 0x80000000u) ? ~b : (b | 0x80000000u); }
;     ...
;     { unsigned u[64];
;       LAS float* srow = sc + wid * 4096;
; #pragma unroll
;       for (int r = 0; r < 64; ++r) { u[r] = 0u; if (r * 64 < n) { const float f = srow[r * 64 + lane]; u[r] = (r * 64 + lane < n) ? sortable(f) : 0u; } }
;     ...
;         if (pref == 0) { int i = (int)atomicAdd(ctr, 1u); if (i < N_D) return i; i = (int)atomicAdd(ctr + 32, 1u); return i < N_ALL - N_D ? q1(i) : N_ALL; }
;         int i = (int)atomicAdd(ctr + 32, 1u); if (i < N_ALL - N_D) return q1(i); i = (int)atomicAdd(ctr, 1u); return i < N_D ? i : N_ALL; };
	v_readlane_b32 vcc_lo, v253, 57
	v_readlane_b32 vcc_hi, v253, 58
	s_nop 3
	s_and_b64 vcc, exec, vcc
	s_cbranch_vccz .Ldf_noissue
	v_cmpx_eq_u32_e32 vcc, 0, v198
	s_nop 4
	s_cbranch_execz .Ldf_issued
	v_readlane_b32 vcc_lo, v253, 55
	v_readlane_b32 vcc_hi, v253, 56
	v_mov_b32_e32 v249, 1
	s_nop 4
	global_atomic_add v249, v1, v249, vcc offset:128 sc0
.Ldf_issued:
	s_mov_b64 exec, -1
.Ldf_noissue:
	v_lshl_add_u32 v0, v163, 2, s60
	v_sub_u32_e32 v2, s61, v163
	ds_read_b32 v6, v0
	ds_read_b32 v5, v0 offset:256
	ds_read_b32 v8, v0 offset:512
	ds_read_b32 v7, v0 offset:768
	ds_read_b32 v10, v0 offset:1024
	ds_read_b32 v9, v0 offset:1280
	ds_read_b32 v12, v0 offset:1536
	ds_read_b32 v11, v0 offset:1792
	ds_read_b32 v14, v0 offset:2048
	ds_read_b32 v13, v0 offset:2304
	ds_read_b32 v16, v0 offset:2560
	ds_read_b32 v15, v0 offset:2816
	ds_read_b32 v18, v0 offset:3072
	ds_read_b32 v17, v0 offset:3328
	ds_read_b32 v20, v0 offset:3584
	s_waitcnt lgkmcnt(0)
	s_cmpk_lt_i32 s61, 0x3c0
	s_cbranch_scc1 .Ludsa_last0
	ds_read_b32 v19, v0 offset:3840
	ds_read_b32 v22, v0 offset:4096
	ds_read_b32 v21, v0 offset:4352
	ds_read_b32 v24, v0 offset:4608
	ds_read_b32 v23, v0 offset:4864
	ds_read_b32 v26, v0 offset:5120
	ds_read_b32 v25, v0 offset:5376
	ds_read_b32 v28, v0 offset:5632
	ds_read_b32 v27, v0 offset:5888
	ds_read_b32 v30, v0 offset:6144
	ds_read_b32 v29, v0 offset:6400
	ds_read_b32 v32, v0 offset:6656
	ds_read_b32 v31, v0 offset:6912
	ds_read_b32 v34, v0 offset:7168
	ds_read_b32 v33, v0 offset:7424
	v_cmp_le_i32_e32 vcc, 0, v2
	v_ashrrev_i32_e32 v4, 31, v6
	v_or_b32_e32 v4, 0x80000000, v4
	v_xor_b32_e32 v6, v4, v6
	v_cndmask_b32_e32 v6, 0, v6, vcc
	v_cmp_le_i32_e32 vcc, 64, v2
	v_ashrrev_i32_e32 v3, 31, v5
	v_or_b32_e32 v3, 0x80000000, v3
	v_xor_b32_e32 v5, v3, v5
	v_cndmask_b32_e32 v5, 0, v5, vcc
	v_cmp_le_i32_e32 vcc, 0x80, v2
	v_ashrrev_i32_e32 v4, 31, v8
	v_or_b32_e32 v4, 0x80000000, v4
	v_xor_b32_e32 v8, v4, v8
	v_cndmask_b32_e32 v8, 0, v8, vcc
	v_cmp_le_i32_e32 vcc, 0xc0, v2
	v_ashrrev_i32_e32 v3, 31, v7
	v_or_b32_e32 v3, 0x80000000, v3
	v_xor_b32_e32 v7, v3, v7
	v_cndmask_b32_e32 v7, 0, v7, vcc
	v_cmp_le_i32_e32 vcc, 0x100, v2
	v_ashrrev_i32_e32 v4, 31, v10
	v_or_b32_e32 v4, 0x80000000, v4
	v_xor_b32_e32 v10, v4, v10
	v_cndmask_b32_e32 v10, 0, v10, vcc
	v_cmp_le_i32_e32 vcc, 0x140, v2
	v_ashrrev_i32_e32 v3, 31, v9
	v_or_b32_e32 v3, 0x80000000, v3
	v_xor_b32_e32 v9, v3, v9
	v_cndmask_b32_e32 v9, 0, v9, vcc
	v_cmp_le_i32_e32 vcc, 0x180, v2
	v_ashrrev_i32_e32 v4, 31, v12
	v_or_b32_e32 v4, 0x80000000, v4
	v_xor_b32_e32 v12, v4, v12
	v_cndmask_b32_e32 v12, 0, v12, vcc
	v_cmp_le_i32_e32 vcc, 0x1c0, v2
	v_ashrrev_i32_e32 v3, 31, v11
	v_or_b32_e32 v3, 0x80000000, v3
	v_xor_b32_e32 v11, v3, v11
	v_cndmask_b32_e32 v11, 0, v11, vcc
	v_cmp_le_i32_e32 vcc, 0x200, v2
	v_ashrrev_i32_e32 v4, 31, v14
	v_or_b32_e32 v4, 0x80000000, v4
	v_xor_b32_e32 v14, v4, v14
	v_cndmask_b32_e32 v14, 0, v14, vcc
	v_cmp_le_i32_e32 vcc, 0x240, v2
	v_ashrrev_i32_e32 v3, 31, v13
	v_or_b32_e32 v3, 0x80000000, v3
	v_xor_b32_e32 v13, v3, v13
	v_cndmask_b32_e32 v13, 0, v13, vcc
	v_cmp_le_i32_e32 vcc, 0x280, v2
	v_ashrrev_i32_e32 v4, 31, v16
	v_or_b32_e32 v4, 0x80000000, v4
	v_xor_b32_e32 v16, v4, v16
	v_cndmask_b32_e32 v16, 0, v16, vcc
	v_cmp_le_i32_e32 vcc, 0x2c0, v2
	v_ashrrev_i32_e32 v3, 31, v15
	v_or_b32_e32 v3, 0x80000000, v3
	v_xor_b32_e32 v15, v3, v15
	v_cndmask_b32_e32 v15, 0, v15, vcc
	v_cmp_le_i32_e32 vcc, 0x300, v2
	v_ashrrev_i32_e32 v4, 31, v18
	v_or_b32_e32 v4, 0x80000000, v4
	v_xor_b32_e32 v18, v4, v18
	v_cndmask_b32_e32 v18, 0, v18, vcc
	v_cmp_le_i32_e32 vcc, 0x340, v2
	v_ashrrev_i32_e32 v3, 31, v17
	v_or_b32_e32 v3, 0x80000000, v3
	v_xor_b32_e32 v17, v3, v17
	v_cndmask_b32_e32 v17, 0, v17, vcc
	v_cmp_le_i32_e32 vcc, 0x380, v2
	v_ashrrev_i32_e32 v4, 31, v20
	v_or_b32_e32 v4, 0x80000000, v4
	v_xor_b32_e32 v20, v4, v20
	v_cndmask_b32_e32 v20, 0, v20, vcc
	s_waitcnt lgkmcnt(0)
	s_cmpk_lt_i32 s61, 0x780
	s_cbranch_scc1 .Ludsa_last1
	ds_read_b32 v36, v0 offset:7680
	ds_read_b32 v35, v0 offset:7936
	ds_read_b32 v38, v0 offset:8192
	ds_read_b32 v37, v0 offset:8448
	ds_read_b32 v40, v0 offset:8704
	ds_read_b32 v39, v0 offset:8960
	ds_read_b32 v42, v0 offset:9216
	ds_read_b32 v41, v0 offset:9472
	ds_read_b32 v44, v0 offset:9728
	ds_read_b32 v43, v0 offset:9984
	ds_read_b32 v46, v0 offset:10240
	ds_read_b32 v45, v0 offset:10496
	ds_read_b32 v48, v0 offset:10752
	ds_read_b32 v47, v0 offset:11008
	ds_read_b32 v50, v0 offset:11264
	v_cmp_le_i32_e32 vcc, 0x3c0, v2
	v_ashrrev_i32_e32 v3, 31, v19
	v_or_b32_e32 v3, 0x80000000, v3
	v_xor_b32_e32 v19, v3, v19
	v_cndmask_b32_e32 v19, 0, v19, vcc
	v_cmp_le_i32_e32 vcc, 0x400, v2
	v_ashrrev_i32_e32 v4, 31, v22
	v_or_b32_e32 v4, 0x80000000, v4
	v_xor_b32_e32 v22, v4, v22
	v_cndmask_b32_e32 v22, 0, v22, vcc
	v_cmp_le_i32_e32 vcc, 0x440, v2
	v_ashrrev_i32_e32 v3, 31, v21
	v_or_b32_e32 v3, 0x80000000, v3
	v_xor_b32_e32 v21, v3, v21
	v_cndmask_b32_e32 v21, 0, v21, vcc
	v_cmp_le_i32_e32 vcc, 0x480, v2
	v_ashrrev_i32_e32 v4, 31, v24
	v_or_b32_e32 v4, 0x80000000, v4
	v_xor_b32_e32 v24, v4, v24
	v_cndmask_b32_e32 v24, 0, v24, vcc
	v_cmp_le_i32_e32 vcc, 0x4c0, v2
	v_ashrrev_i32_e32 v3, 31, v23
	v_or_b32_e32 v3, 0x80000000, v3
	v_xor_b32_e32 v23, v3, v23
	v_cndmask_b32_e32 v23, 0, v23, vcc
	v_cmp_le_i32_e32 vcc, 0x500, v2
	v_ashrrev_i32_e32 v4, 31, v26
	v_or_b32_e32 v4, 0x80000000, v4
	v_xor_b32_e32 v26, v4, v26
	v_cndmask_b32_e32 v26, 0, v26, vcc
	v_cmp_le_i32_e32 vcc, 0x540, v2
	v_ashrrev_i32_e32 v3, 31, v25
	v_or_b32_e32 v3, 0x80000000, v3
	v_xor_b32_e32 v25, v3, v25
	v_cndmask_b32_e32 v25, 0, v25, vcc
	v_cmp_le_i32_e32 vcc, 0x580, v2
	v_ashrrev_i32_e32 v4, 31, v28
	v_or_b32_e32 v4, 0x80000000, v4
	v_xor_b32_e32 v28, v4, v28
	v_cndmask_b32_e32 v28, 0, v28, vcc
	v_cmp_le_i32_e32 vcc, 0x5c0, v2
	v_ashrrev_i32_e32 v3, 31, v27
	v_or_b32_e32 v3, 0x80000000, v3
	v_xor_b32_e32 v27, v3, v27
	v_cndmask_b32_e32 v27, 0, v27, vcc
	v_cmp_le_i32_e32 vcc, 0x600, v2
	v_ashrrev_i32_e32 v4, 31, v30
	v_or_b32_e32 v4, 0x80000000, v4
	v_xor_b32_e32 v30, v4, v30
	v_cndmask_b32_e32 v30, 0, v30, vcc
	v_cmp_le_i32_e32 vcc, 0x640, v2
	v_ashrrev_i32_e32 v3, 31, v29
	v_or_b32_e32 v3, 0x80000000, v3
	v_xor_b32_e32 v29, v3, v29
	v_cndmask_b32_e32 v29, 0, v29, vcc
	v_cmp_le_i32_e32 vcc, 0x680, v2
	v_ashrrev_i32_e32 v4, 31, v32
	v_or_b32_e32 v4, 0x80000000, v4
	v_xor_b32_e32 v32, v4, v32
	v_cndmask_b32_e32 v32, 0, v32, vcc
	v_cmp_le_i32_e32 vcc, 0x6c0, v2
	v_ashrrev_i32_e32 v3, 31, v31
	v_or_b32_e32 v3, 0x80000000, v3
	v_xor_b32_e32 v31, v3, v31
	v_cndmask_b32_e32 v31, 0, v31, vcc
	v_cmp_le_i32_e32 vcc, 0x700, v2
	v_ashrrev_i32_e32 v4, 31, v34
	v_or_b32_e32 v4, 0x80000000, v4
	v_xor_b32_e32 v34, v4, v34
	v_cndmask_b32_e32 v34, 0, v34, vcc
	v_cmp_le_i32_e32 vcc, 0x740, v2
	v_ashrrev_i32_e32 v3, 31, v33
	v_or_b32_e32 v3, 0x80000000, v3
	v_xor_b32_e32 v33, v3, v33
	v_cndmask_b32_e32 v33, 0, v33, vcc
	s_waitcnt lgkmcnt(0)
	s_cmpk_lt_i32 s61, 0xb40
	s_cbranch_scc1 .Ludsa_last2
; __device__ __forceinline__ unsigned sortable(float f) { const unsigned b = __float_as_uint(f); return (b & 0x80000000u) ? ~b : (b | 0x80000000u); }
;     ...
; #pragma unroll
;       for (int r = 0; r < 64; ++r) { u[r] = 0u; if (r * 64 < n) { const float f = srow[r * 64 + lane]; u[r] = (r * 64 + lane < n) ? sortable(f) : 0u; } }
	ds_read_b32 v49, v0 offset:11520
	ds_read_b32 v52, v0 offset:11776
	ds_read_b32 v51, v0 offset:12032
	ds_read_b32 v54, v0 offset:12288
	ds_read_b32 v53, v0 offset:12544
	ds_read_b32 v56, v0 offset:12800
	ds_read_b32 v55, v0 offset:13056
	ds_read_b32 v58, v0 offset:13312
	ds_read_b32 v57, v0 offset:13568
	ds_read_b32 v60, v0 offset:13824
	ds_read_b32 v59, v0 offset:14080
	ds_read_b32 v62, v0 offset:14336
	ds_read_b32 v61, v0 offset:14592
	ds_read_b32 v64, v0 offset:14848
	ds_read_b32 v63, v0 offset:15104
	v_cmp_le_i32_e32 vcc, 0x780, v2
	v_ashrrev_i32_e32 v4, 31, v36
	v_or_b32_e32 v4, 0x80000000, v4
	v_xor_b32_e32 v36, v4, v36
	v_cndmask_b32_e32 v36, 0, v36, vcc
	v_cmp_le_i32_e32 vcc, 0x7c0, v2
	v_ashrrev_i32_e32 v3, 31, v35
	v_or_b32_e32 v3, 0x80000000, v3
	v_xor_b32_e32 v35, v3, v35
	v_cndmask_b32_e32 v35, 0, v35, vcc
	v_cmp_le_i32_e32 vcc, 0x800, v2
	v_ashrrev_i32_e32 v4, 31, v38
	v_or_b32_e32 v4, 0x80000000, v4
	v_xor_b32_e32 v38, v4, v38
	v_cndmask_b32_e32 v38, 0, v38, vcc
	v_cmp_le_i32_e32 vcc, 0x840, v2
	v_ashrrev_i32_e32 v3, 31, v37
	v_or_b32_e32 v3, 0x80000000, v3
	v_xor_b32_e32 v37, v3, v37
	v_cndmask_b32_e32 v37, 0, v37, vcc
	v_cmp_le_i32_e32 vcc, 0x880, v2
	v_ashrrev_i32_e32 v4, 31, v40
	v_or_b32_e32 v4, 0x80000000, v4
	v_xor_b32_e32 v40, v4, v40
	v_cndmask_b32_e32 v40, 0, v40, vcc
	v_cmp_le_i32_e32 vcc, 0x8c0, v2
	v_ashrrev_i32_e32 v3, 31, v39
	v_or_b32_e32 v3, 0x80000000, v3
	v_xor_b32_e32 v39, v3, v39
	v_cndmask_b32_e32 v39, 0, v39, vcc
	v_cmp_le_i32_e32 vcc, 0x900, v2
	v_ashrrev_i32_e32 v4, 31, v42
	v_or_b32_e32 v4, 0x80000000, v4
	v_xor_b32_e32 v42, v4, v42
	v_cndmask_b32_e32 v42, 0, v42, vcc
	v_cmp_le_i32_e32 vcc, 0x940, v2
	v_ashrrev_i32_e32 v3, 31, v41
	v_or_b32_e32 v3, 0x80000000, v3
	v_xor_b32_e32 v41, v3, v41
	v_cndmask_b32_e32 v41, 0, v41, vcc
	v_cmp_le_i32_e32 vcc, 0x980, v2
	v_ashrrev_i32_e32 v4, 31, v44
	v_or_b32_e32 v4, 0x80000000, v4
	v_xor_b32_e32 v44, v4, v44
	v_cndmask_b32_e32 v44, 0, v44, vcc
	v_cmp_le_i32_e32 vcc, 0x9c0, v2
	v_ashrrev_i32_e32 v3, 31, v43
	v_or_b32_e32 v3, 0x80000000, v3
	v_xor_b32_e32 v43, v3, v43
	v_cndmask_b32_e32 v43, 0, v43, vcc
	v_cmp_le_i32_e32 vcc, 0xa00, v2
	v_ashrrev_i32_e32 v4, 31, v46
	v_or_b32_e32 v4, 0x80000000, v4
	v_xor_b32_e32 v46, v4, v46
	v_cndmask_b32_e32 v46, 0, v46, vcc
	v_cmp_le_i32_e32 vcc, 0xa40, v2
	v_ashrrev_i32_e32 v3, 31, v45
	v_or_b32_e32 v3, 0x80000000, v3
	v_xor_b32_e32 v45, v3, v45
	v_cndmask_b32_e32 v45, 0, v45, vcc
	v_cmp_le_i32_e32 vcc, 0xa80, v2
	v_ashrrev_i32_e32 v4, 31, v48
	v_or_b32_e32 v4, 0x80000000, v4
	v_xor_b32_e32 v48, v4, v48
	v_cndmask_b32_e32 v48, 0, v48, vcc
	v_cmp_le_i32_e32 vcc, 0xac0, v2
	v_ashrrev_i32_e32 v3, 31, v47
	v_or_b32_e32 v3, 0x80000000, v3
	v_xor_b32_e32 v47, v3, v47
	v_cndmask_b32_e32 v47, 0, v47, vcc
	v_cmp_le_i32_e32 vcc, 0xb00, v2
	v_ashrrev_i32_e32 v4, 31, v50
	v_or_b32_e32 v4, 0x80000000, v4
	v_xor_b32_e32 v50, v4, v50
	v_cndmask_b32_e32 v50, 0, v50, vcc
	s_waitcnt lgkmcnt(0)
	s_cmpk_lt_i32 s61, 0xf00
	s_cbranch_scc1 .Ludsa_last3
	ds_read_b32 v66, v0 offset:15360
	ds_read_b32 v65, v0 offset:15616
	ds_read_b32 v68, v0 offset:15872
	ds_read_b32 v67, v0 offset:16128
	v_cmp_le_i32_e32 vcc, 0xb40, v2
	v_ashrrev_i32_e32 v3, 31, v49
	v_or_b32_e32 v3, 0x80000000, v3
	v_xor_b32_e32 v49, v3, v49
	v_cndmask_b32_e32 v49, 0, v49, vcc
	v_cmp_le_i32_e32 vcc, 0xb80, v2
	v_ashrrev_i32_e32 v4, 31, v52
	v_or_b32_e32 v4, 0x80000000, v4
	v_xor_b32_e32 v52, v4, v52
	v_cndmask_b32_e32 v52, 0, v52, vcc
	v_cmp_le_i32_e32 vcc, 0xbc0, v2
	v_ashrrev_i32_e32 v3, 31, v51
	v_or_b32_e32 v3, 0x80000000, v3
	v_xor_b32_e32 v51, v3, v51
	v_cndmask_b32_e32 v51, 0, v51, vcc
	v_cmp_le_i32_e32 vcc, 0xc00, v2
	v_ashrrev_i32_e32 v4, 31, v54
	v_or_b32_e32 v4, 0x80000000, v4
	v_xor_b32_e32 v54, v4, v54
	v_cndmask_b32_e32 v54, 0, v54, vcc
	v_cmp_le_i32_e32 vcc, 0xc40, v2
	v_ashrrev_i32_e32 v3, 31, v53
	v_or_b32_e32 v3, 0x80000000, v3
	v_xor_b32_e32 v53, v3, v53
	v_cndmask_b32_e32 v53, 0, v53, vcc
	v_cmp_le_i32_e32 vcc, 0xc80, v2
	v_ashrrev_i32_e32 v4, 31, v56
	v_or_b32_e32 v4, 0x80000000, v4
	v_xor_b32_e32 v56, v4, v56
	v_cndmask_b32_e32 v56, 0, v56, vcc
	v_cmp_le_i32_e32 vcc, 0xcc0, v2
	v_ashrrev_i32_e32 v3, 31, v55
	v_or_b32_e32 v3, 0x80000000, v3
	v_xor_b32_e32 v55, v3, v55
	v_cndmask_b32_e32 v55, 0, v55, vcc
	v_cmp_le_i32_e32 vcc, 0xd00, v2
	v_ashrrev_i32_e32 v4, 31, v58
	v_or_b32_e32 v4, 0x80000000, v4
	v_xor_b32_e32 v58, v4, v58
	v_cndmask_b32_e32 v58, 0, v58, vcc
	v_cmp_le_i32_e32 vcc, 0xd40, v2
	v_ashrrev_i32_e32 v3, 31, v57
	v_or_b32_e32 v3, 0x80000000, v3
	v_xor_b32_e32 v57, v3, v57
	v_cndmask_b32_e32 v57, 0, v57, vcc
	v_cmp_le_i32_e32 vcc, 0xd80, v2
	v_ashrrev_i32_e32 v4, 31, v60
	v_or_b32_e32 v4, 0x80000000, v4
	v_xor_b32_e32 v60, v4, v60
	v_cndmask_b32_e32 v60, 0, v60, vcc
	v_cmp_le_i32_e32 vcc, 0xdc0, v2
	v_ashrrev_i32_e32 v3, 31, v59
	v_or_b32_e32 v3, 0x80000000, v3
	v_xor_b32_e32 v59, v3, v59
	v_cndmask_b32_e32 v59, 0, v59, vcc
	v_cmp_le_i32_e32 vcc, 0xe00, v2
	v_ashrrev_i32_e32 v4, 31, v62
	v_or_b32_e32 v4, 0x80000000, v4
	v_xor_b32_e32 v62, v4, v62
	v_cndmask_b32_e32 v62, 0, v62, vcc
	v_cmp_le_i32_e32 vcc, 0xe40, v2
	v_ashrrev_i32_e32 v3, 31, v61
	v_or_b32_e32 v3, 0x80000000, v3
	v_xor_b32_e32 v61, v3, v61
	v_cndmask_b32_e32 v61, 0, v61, vcc
	v_cmp_le_i32_e32 vcc, 0xe80, v2
	v_ashrrev_i32_e32 v4, 31, v64
	v_or_b32_e32 v4, 0x80000000, v4
	v_xor_b32_e32 v64, v4, v64
	v_cndmask_b32_e32 v64, 0, v64, vcc
	v_cmp_le_i32_e32 vcc, 0xec0, v2
	v_ashrrev_i32_e32 v3, 31, v63
	v_or_b32_e32 v3, 0x80000000, v3
	v_xor_b32_e32 v63, v3, v63
	v_cndmask_b32_e32 v63, 0, v63, vcc
	s_waitcnt lgkmcnt(0)
	v_cmp_le_i32_e32 vcc, 0xf00, v2
	v_ashrrev_i32_e32 v4, 31, v66
	v_or_b32_e32 v4, 0x80000000, v4
	v_xor_b32_e32 v66, v4, v66
	v_cndmask_b32_e32 v66, 0, v66, vcc
	v_cmp_le_i32_e32 vcc, 0xf40, v2
	v_ashrrev_i32_e32 v3, 31, v65
	v_or_b32_e32 v3, 0x80000000, v3
	v_xor_b32_e32 v65, v3, v65
	v_cndmask_b32_e32 v65, 0, v65, vcc
	v_cmp_le_i32_e32 vcc, 0xf80, v2
	v_ashrrev_i32_e32 v4, 31, v68
	v_or_b32_e32 v4, 0x80000000, v4
	v_xor_b32_e32 v68, v4, v68
	v_cndmask_b32_e32 v68, 0, v68, vcc
	v_cmp_le_i32_e32 vcc, 0xfc0, v2
	v_ashrrev_i32_e32 v3, 31, v67
	v_or_b32_e32 v3, 0x80000000, v3
	v_xor_b32_e32 v67, v3, v67
	v_cndmask_b32_e32 v67, 0, v67, vcc
	s_branch .Ludsa_done

;     ...
;         auto q1 = [&](int i) -> int { return i < N_A + N_C ? N_D + N_B + i : N_D + (i - (N_A + N_C)); };
;         if (pref == 0) { int i = (int)atomicAdd(ctr, 1u); if (i < N_D) return i; i = (int)atomicAdd(ctr + 32, 1u); return i < N_ALL - N_D ? q1(i) : N_ALL; }
;         int i = (int)atomicAdd(ctr + 32, 1u); if (i < N_ALL - N_D) return q1(i); i = (int)atomicAdd(ctr, 1u); return i < N_D ? i : N_ALL; };
;     ...
;         if (threadIdx.x == 0 && it < N_ALL) nxt = fetch();
.LBB0_926:
	v_readlane_b32 vcc_lo, v253, 57
	v_readlane_b32 vcc_hi, v253, 58
	s_nop 3
	s_and_b64 vcc, exec, vcc
	s_cbranch_vccz .Ldf_done
	s_waitcnt vmcnt(0)
	v_cmpx_eq_u32_e32 vcc, 0, v198
	s_nop 4
	s_cbranch_execz .Ldf_fin
	v_add_u32_e32 v248, 0x900, v249
	v_cmp_gt_i32_e32 vcc, 0x100, v249
	s_nop 1
	v_cndmask_b32_e32 v180, v249, v248, vcc
	v_cmp_lt_i32_e32 vcc, 0x8ff, v249
	s_nop 1
	s_cbranch_vccz .Ldf_fin
	v_readlane_b32 vcc_lo, v253, 55
	v_readlane_b32 vcc_hi, v253, 56
	v_mov_b32_e32 v249, 1
	s_nop 4
	global_atomic_add v249, v1, v249, vcc sc0
	s_waitcnt vmcnt(0)
	v_cmp_gt_i32_e32 vcc, 0x100, v249
	s_nop 1
	v_cndmask_b32_e32 v180, v204, v249, vcc
